# v16 + attention output stage: 15 serial weight loads issued behind the first one, one wait before the first store, none between stores
# speedup vs baseline: 1.0028x; 1.0017x over previous
; #define LAS __attribute__((address_space(3)))
; DI void attn_unit(LAS unsigned char* lds, int tid, const bf16* __restrict__ P, const bf16* __restrict__ Vt, bf16* MG, int b, int h, int qrow0, int jt0, int jt1,
;                   float lam, float oscale, const float* subg) {
;     ...
;     __syncthreads();
;     const float l = lrun + __shfl_xor(lrun, 32);
;     const float inv = (m ? lam : 1.0f) / l;
;     LAS float* X = (LAS float*)lds + qb * 4096 + lane;
;     if (m) {
; #pragma unroll
;         for (int es = 0; es < 4; ++es)
; #pragma unroll
;             for (int i = 0; i < 16; ++i) X[(es * 16 + i) * 64] = O[es][i] * inv;
;     }
;     __syncthreads();
;     if (!m) {
;         float ss = 0.f;
; #pragma unroll
;         for (int es = 0; es < 4; ++es)
; #pragma unroll
;             for (int i = 0; i < 16; ++i) { const float o = O[es][i] * inv - X[(es * 16 + i) * 64]; O[es][i] = o; ss += o * o; }
.LBB0_316:
	s_or_b64 exec, exec, s[2:3]
	s_waitcnt lgkmcnt(0)
	s_barrier
	s_and_saveexec_b64 s[2:3], s[0:1]
	s_cbranch_execz .LBB0_294
	ds_read2st64_b32 v[88:89], v82 offset1:1
	ds_read2st64_b32 v[90:91], v82 offset0:2 offset1:3
	ds_read2st64_b32 v[104:105], v82 offset0:4 offset1:5
	ds_read2st64_b32 v[96:97], v82 offset0:6 offset1:7
	ds_read2st64_b32 v[106:107], v82 offset0:8 offset1:9
	s_waitcnt vmcnt(2)
	ds_read2st64_b32 v[132:133], v82 offset0:10 offset1:11
	ds_read2st64_b32 v[128:129], v82 offset0:12 offset1:13
	ds_read2st64_b32 v[134:135], v82 offset0:14 offset1:15
	ds_read2st64_b32 v[124:125], v82 offset0:16 offset1:17
	ds_read2st64_b32 v[130:131], v82 offset0:18 offset1:19
	ds_read2st64_b32 v[120:121], v82 offset0:20 offset1:21
	ds_read2st64_b32 v[126:127], v82 offset0:22 offset1:23
	ds_read2st64_b32 v[116:117], v82 offset0:24 offset1:25
	ds_read2st64_b32 v[122:123], v82 offset0:26 offset1:27
	ds_read2st64_b32 v[112:113], v82 offset0:28 offset1:29
	ds_read2st64_b32 v[118:119], v82 offset0:30 offset1:31
	ds_read2st64_b32 v[102:103], v82 offset0:32 offset1:33
	ds_read2st64_b32 v[114:115], v82 offset0:34 offset1:35
	ds_read2st64_b32 v[98:99], v82 offset0:36 offset1:37
	ds_read2st64_b32 v[108:109], v82 offset0:38 offset1:39
	ds_read2st64_b32 v[92:93], v82 offset0:40 offset1:41
	ds_read2st64_b32 v[100:101], v82 offset0:42 offset1:43
	ds_read2st64_b32 v[86:87], v82 offset0:44 offset1:45
	ds_read2st64_b32 v[94:95], v82 offset0:46 offset1:47
	ds_read2st64_b32 v[80:81], v82 offset0:48 offset1:49
	ds_read2st64_b32 v[84:85], v82 offset0:50 offset1:51
	ds_read2st64_b32 v[76:77], v82 offset0:52 offset1:53
	ds_read2st64_b32 v[78:79], v82 offset0:54 offset1:55
	ds_read2st64_b32 v[72:73], v82 offset0:56 offset1:57
	ds_read2st64_b32 v[64:65], v82 offset0:58 offset1:59
	s_waitcnt lgkmcnt(14)
	v_pk_fma_f32 v[96:97], v[54:55], v[68:69], v[96:97] op_sel_hi:[1,0,1] neg_lo:[0,0,1] neg_hi:[0,0,1]
	v_pk_fma_f32 v[104:105], v[52:53], v[68:69], v[104:105] op_sel_hi:[1,0,1] neg_lo:[0,0,1] neg_hi:[0,0,1]
	v_pk_fma_f32 v[106:107], v[56:57], v[68:69], v[106:107] op_sel_hi:[1,0,1] neg_lo:[0,0,1] neg_hi:[0,0,1]
	v_pk_fma_f32 v[62:63], v[62:63], v[68:69], v[134:135] op_sel_hi:[1,0,1] neg_lo:[0,0,1] neg_hi:[0,0,1]
	s_waitcnt lgkmcnt(0)
	v_pk_fma_f32 v[64:65], v[10:11], v[68:69], v[64:65] op_sel_hi:[1,0,1] neg_lo:[0,0,1] neg_hi:[0,0,1]
	ds_read2st64_b32 v[10:11], v82 offset0:60 offset1:61
	v_pk_fma_f32 v[60:61], v[60:61], v[68:69], v[128:129] op_sel_hi:[1,0,1] neg_lo:[0,0,1] neg_hi:[0,0,1]
	v_pk_fma_f32 v[56:57], v[34:35], v[68:69], v[130:131] op_sel_hi:[1,0,1] neg_lo:[0,0,1] neg_hi:[0,0,1]
	v_pk_fma_f32 v[54:55], v[36:37], v[68:69], v[120:121] op_sel_hi:[1,0,1] neg_lo:[0,0,1] neg_hi:[0,0,1]
	v_pk_fma_f32 v[42:43], v[42:43], v[68:69], v[122:123] op_sel_hi:[1,0,1] neg_lo:[0,0,1] neg_hi:[0,0,1]
	s_waitcnt lgkmcnt(0)
	v_pk_fma_f32 v[66:67], v[12:13], v[68:69], v[10:11] op_sel_hi:[1,0,1] neg_lo:[0,0,1] neg_hi:[0,0,1]
	ds_read2st64_b32 v[10:11], v82 offset0:62 offset1:63
	v_pk_fma_f32 v[82:83], v[50:51], v[68:69], v[90:91] op_sel_hi:[1,0,1] neg_lo:[0,0,1] neg_hi:[0,0,1]
	v_pk_fma_f32 v[90:91], v[48:49], v[68:69], v[88:89] op_sel_hi:[1,0,1] neg_lo:[0,0,1] neg_hi:[0,0,1]
	s_waitcnt vmcnt(1)
	v_pk_mul_f32 v[138:139], v[82:83], v[82:83]
	s_waitcnt vmcnt(0)
	v_pk_mul_f32 v[140:141], v[90:91], v[90:91]
	s_waitcnt lgkmcnt(0)
	v_pk_fma_f32 v[14:15], v[14:15], v[68:69], v[10:11] op_sel_hi:[1,0,1] neg_lo:[0,0,1] neg_hi:[0,0,1]
	v_pk_fma_f32 v[88:89], v[58:59], v[68:69], v[132:133] op_sel_hi:[1,0,1] neg_lo:[0,0,1] neg_hi:[0,0,1]
	v_pk_fma_f32 v[58:59], v[32:33], v[68:69], v[124:125] op_sel_hi:[1,0,1] neg_lo:[0,0,1] neg_hi:[0,0,1]
	v_pk_fma_f32 v[50:51], v[38:39], v[68:69], v[126:127] op_sel_hi:[1,0,1] neg_lo:[0,0,1] neg_hi:[0,0,1]
	v_pk_fma_f32 v[52:53], v[40:41], v[68:69], v[116:117] op_sel_hi:[1,0,1] neg_lo:[0,0,1] neg_hi:[0,0,1]
	v_pk_fma_f32 v[40:41], v[46:47], v[68:69], v[118:119] op_sel_hi:[1,0,1] neg_lo:[0,0,1] neg_hi:[0,0,1]
	v_pk_fma_f32 v[44:45], v[44:45], v[68:69], v[112:113] op_sel_hi:[1,0,1] neg_lo:[0,0,1] neg_hi:[0,0,1]
	v_pk_fma_f32 v[36:37], v[18:19], v[68:69], v[114:115] op_sel_hi:[1,0,1] neg_lo:[0,0,1] neg_hi:[0,0,1]
	v_pk_fma_f32 v[38:39], v[16:17], v[68:69], v[102:103] op_sel_hi:[1,0,1] neg_lo:[0,0,1] neg_hi:[0,0,1]
	v_pk_fma_f32 v[32:33], v[22:23], v[68:69], v[108:109] op_sel_hi:[1,0,1] neg_lo:[0,0,1] neg_hi:[0,0,1]
	v_pk_fma_f32 v[34:35], v[20:21], v[68:69], v[98:99] op_sel_hi:[1,0,1] neg_lo:[0,0,1] neg_hi:[0,0,1]
	v_pk_fma_f32 v[22:23], v[26:27], v[68:69], v[100:101] op_sel_hi:[1,0,1] neg_lo:[0,0,1] neg_hi:[0,0,1]
	v_pk_fma_f32 v[26:27], v[24:25], v[68:69], v[92:93] op_sel_hi:[1,0,1] neg_lo:[0,0,1] neg_hi:[0,0,1]
	v_pk_fma_f32 v[20:21], v[30:31], v[68:69], v[94:95] op_sel_hi:[1,0,1] neg_lo:[0,0,1] neg_hi:[0,0,1]
	v_pk_fma_f32 v[24:25], v[28:29], v[68:69], v[86:87] op_sel_hi:[1,0,1] neg_lo:[0,0,1] neg_hi:[0,0,1]
	v_pk_fma_f32 v[16:17], v[2:3], v[68:69], v[84:85] op_sel_hi:[1,0,1] neg_lo:[0,0,1] neg_hi:[0,0,1]
	v_pk_fma_f32 v[18:19], v[0:1], v[68:69], v[80:81] op_sel_hi:[1,0,1] neg_lo:[0,0,1] neg_hi:[0,0,1]
	v_pk_fma_f32 v[2:3], v[6:7], v[68:69], v[78:79] op_sel_hi:[1,0,1] neg_lo:[0,0,1] neg_hi:[0,0,1]
	v_pk_fma_f32 v[4:5], v[4:5], v[68:69], v[76:77] op_sel_hi:[1,0,1] neg_lo:[0,0,1] neg_hi:[0,0,1]
	v_pk_fma_f32 v[0:1], v[8:9], v[68:69], v[72:73] op_sel_hi:[1,0,1] neg_lo:[0,0,1] neg_hi:[0,0,1]
	v_add_f32_e32 v68, v140, v141
	v_lshlrev_b64 v[10:11], 11, v[156:157]
	v_readlane_b32 s16, v253, 6
	v_add_f32_e32 v68, v68, v138
	v_lshl_add_u64 v[10:11], s[70:71], 0, v[10:11]
	v_readlane_b32 s17, v253, 7
	v_pk_mul_f32 v[142:143], v[104:105], v[104:105]
; DI void attn_unit(LAS unsigned char* lds, int tid, const bf16* __restrict__ P, const bf16* __restrict__ Vt, bf16* MG, int b, int h, int qrow0, int jt0, int jt1,
;                   float lam, float oscale, const float* subg) {
;     ...
;         float ss = 0.f;
; #pragma unroll
;         for (int es = 0; es < 4; ++es)
; #pragma unroll
;             for (int i = 0; i < 16; ++i) { const float o = O[es][i] * inv - X[(es * 16 + i) * 64]; O[es][i] = o; ss += o * o; }
;         ss += __shfl_xor(ss, 32);
;         const float rn = (1.0f / sqrtf(ss * (1.0f / 128.0f) + 1e-6f)) * oscale;
; #pragma unroll
;         for (int es = 0; es < 4; ++es)
; #pragma unroll
;             for (int g4 = 0; g4 < 4; ++g4) {
;                 const int e = es * 32 + 8 * g4 + 4 * hi;
;                 const f32x4 gv = *(const f32x4*)(subg + e);
	v_add_f32_e32 v68, v68, v139
	v_lshl_add_u64 v[136:137], v[10:11], 0, s[16:17]
	v_lshlrev_b32_e32 v146, 3, v167
	v_add_f32_e32 v68, v68, v142
	v_lshl_add_u64 v[48:49], v[136:137], 0, v[146:147]
	v_pk_mul_f32 v[136:137], v[96:97], v[96:97]
	v_add_f32_e32 v68, v68, v143
	v_add_f32_e32 v68, v68, v136
	v_pk_mul_f32 v[150:151], v[106:107], v[106:107]
	v_add_f32_e32 v68, v68, v137
	v_add_f32_e32 v68, v68, v150
	v_pk_mul_f32 v[132:133], v[88:89], v[88:89]
	v_add_f32_e32 v68, v68, v151
	v_add_f32_e32 v68, v68, v132
	v_pk_mul_f32 v[128:129], v[60:61], v[60:61]
	v_add_f32_e32 v68, v68, v133
	v_add_f32_e32 v68, v68, v128
	v_pk_mul_f32 v[134:135], v[62:63], v[62:63]
	v_add_f32_e32 v68, v68, v129
	v_add_f32_e32 v68, v68, v134
	v_pk_mul_f32 v[124:125], v[58:59], v[58:59]
	v_add_f32_e32 v68, v68, v135
	v_add_f32_e32 v68, v68, v124
	v_pk_mul_f32 v[130:131], v[56:57], v[56:57]
	v_add_f32_e32 v68, v68, v125
	v_add_f32_e32 v68, v68, v130
	v_readlane_b32 s4, v253, 47
	v_pk_mul_f32 v[120:121], v[54:55], v[54:55]
	v_add_f32_e32 v68, v68, v131
	v_readlane_b32 s5, v253, 48
	v_add_f32_e32 v68, v68, v120
	v_pk_mul_f32 v[126:127], v[50:51], v[50:51]
	v_add_f32_e32 v68, v68, v121
	v_add_f32_e32 v68, v68, v126
	v_pk_mul_f32 v[116:117], v[52:53], v[52:53]
	global_load_dwordx4 v[10:13], v154, s[4:5]
	global_load_dwordx4 v[168:171], v154, s[4:5] offset:32
	global_load_dwordx4 v[172:175], v154, s[4:5] offset:64
	global_load_dwordx4 v[176:179], v154, s[4:5] offset:96
	global_load_dwordx4 v[180:183], v154, s[4:5] offset:128
	global_load_dwordx4 v[184:187], v154, s[4:5] offset:160
	global_load_dwordx4 v[188:191], v154, s[4:5] offset:192
	global_load_dwordx4 v[192:195], v154, s[4:5] offset:224
	global_load_dwordx4 v[196:199], v154, s[4:5] offset:256
	global_load_dwordx4 v[200:203], v154, s[4:5] offset:288
	global_load_dwordx4 v[204:207], v154, s[4:5] offset:320
	global_load_dwordx4 v[218:221], v154, s[4:5] offset:352
	global_load_dwordx4 v[222:225], v154, s[4:5] offset:384
	global_load_dwordx4 v[226:229], v154, s[4:5] offset:416
	global_load_dwordx4 v[230:233], v154, s[4:5] offset:448
	global_load_dwordx4 v[234:237], v154, s[4:5] offset:480
	v_add_f32_e32 v68, v68, v127
	v_add_f32_e32 v68, v68, v116
	v_pk_mul_f32 v[122:123], v[42:43], v[42:43]
	v_add_f32_e32 v68, v68, v117
	v_add_f32_e32 v68, v68, v122
	v_pk_mul_f32 v[112:113], v[44:45], v[44:45]
	v_add_f32_e32 v68, v68, v123
	v_add_f32_e32 v68, v68, v112
	v_pk_mul_f32 v[46:47], v[40:41], v[40:41]
	v_add_f32_e32 v68, v68, v113
	v_add_f32_e32 v46, v68, v46
	v_pk_mul_f32 v[102:103], v[38:39], v[38:39]
	v_add_f32_e32 v46, v46, v47
	v_add_f32_e32 v46, v46, v102
	v_pk_mul_f32 v[114:115], v[36:37], v[36:37]
	v_add_f32_e32 v46, v46, v103
	v_add_f32_e32 v46, v46, v114
	v_pk_mul_f32 v[98:99], v[34:35], v[34:35]
	v_add_f32_e32 v46, v46, v115
	v_add_f32_e32 v46, v46, v98
	v_pk_mul_f32 v[108:109], v[32:33], v[32:33]
	v_add_f32_e32 v46, v46, v99
	v_add_f32_e32 v46, v46, v108
	v_pk_mul_f32 v[92:93], v[26:27], v[26:27]
	v_add_f32_e32 v46, v46, v109
	v_add_f32_e32 v46, v46, v92
	v_pk_mul_f32 v[100:101], v[22:23], v[22:23]
	v_add_f32_e32 v46, v46, v93
	v_add_f32_e32 v46, v46, v100
	v_pk_mul_f32 v[28:29], v[24:25], v[24:25]
	v_add_f32_e32 v46, v46, v101
	v_add_f32_e32 v28, v46, v28
	v_pk_mul_f32 v[30:31], v[20:21], v[20:21]
	v_add_f32_e32 v28, v28, v29
	v_add_f32_e32 v28, v28, v30
	v_pk_mul_f32 v[80:81], v[18:19], v[18:19]
	v_add_f32_e32 v28, v28, v31
	v_add_f32_e32 v28, v28, v80
	v_pk_mul_f32 v[84:85], v[16:17], v[16:17]
	v_add_f32_e32 v28, v28, v81
	v_add_f32_e32 v28, v28, v84
	v_pk_mul_f32 v[76:77], v[4:5], v[4:5]
	v_add_f32_e32 v28, v28, v85
	v_add_f32_e32 v28, v28, v76
	v_pk_mul_f32 v[6:7], v[2:3], v[2:3]
	v_add_f32_e32 v28, v28, v77
	v_add_f32_e32 v6, v28, v6
	v_pk_mul_f32 v[8:9], v[0:1], v[0:1]
	v_add_f32_e32 v6, v6, v7
	v_add_f32_e32 v6, v6, v8
	v_pk_mul_f32 v[70:71], v[64:65], v[64:65]
	v_add_f32_e32 v6, v6, v9
	v_add_f32_e32 v6, v6, v70
	v_pk_mul_f32 v[74:75], v[66:67], v[66:67]
	v_add_f32_e32 v6, v6, v71
	v_add_f32_e32 v6, v6, v74
	v_pk_mul_f32 v[110:111], v[14:15], v[14:15]
	v_add_f32_e32 v6, v6, v75
	v_add_f32_e32 v6, v6, v110
	v_add_f32_e32 v6, v6, v111
	ds_bpermute_b32 v7, v69, v6
	v_readlane_b32 s18, v253, 8
	v_readlane_b32 s19, v253, 9
	v_readlane_b32 s20, v253, 10
	v_readlane_b32 s21, v253, 11
	s_waitcnt lgkmcnt(0)
	v_add_f32_e32 v6, v6, v7
	v_mov_b32_e32 v7, 0x358637bd
	v_fmamk_f32 v6, v6, 0x3c000000, v7
	v_cmp_gt_f32_e32 vcc, s65, v6
	v_mul_f32_e32 v7, 0x4f800000, v6
	v_readlane_b32 s22, v253, 12
	v_cndmask_b32_e32 v6, v6, v7, vcc
	v_sqrt_f32_e32 v7, v6
	v_readlane_b32 s23, v253, 13
	v_readlane_b32 s24, v253, 14
	v_readlane_b32 s25, v253, 15
	v_add_u32_e32 v8, -1, v7
	v_fma_f32 v9, -v8, v7, v6
	v_cmp_ge_f32_e64 s[0:1], 0, v9
	v_add_u32_e32 v9, 1, v7
	v_readlane_b32 s26, v253, 16
	v_cndmask_b32_e64 v8, v7, v8, s[0:1]
	v_fma_f32 v7, -v9, v7, v6
	v_cmp_lt_f32_e64 s[0:1], 0, v7
	v_readlane_b32 s27, v253, 17
	v_readlane_b32 s28, v253, 18
	v_cndmask_b32_e64 v7, v8, v9, s[0:1]
	v_mul_f32_e32 v8, 0x37800000, v7
	v_cndmask_b32_e32 v7, v7, v8, vcc
	v_cmp_class_f32_e32 vcc, v6, v208
	v_readlane_b32 s29, v253, 19
	v_readlane_b32 s30, v253, 20
	v_cndmask_b32_e32 v6, v7, v6, vcc
	v_div_scale_f32 v7, s[0:1], v6, v6, 1.0
	v_rcp_f32_e32 v8, v7
	v_readlane_b32 s31, v253, 21
	v_fma_f32 v9, -v7, v8, 1.0
	v_fmac_f32_e32 v8, v9, v8
	v_div_scale_f32 v9, vcc, 1.0, v6, 1.0
	v_mul_f32_e32 v28, v9, v8
	v_fma_f32 v29, -v7, v28, v9
	v_fmac_f32_e32 v28, v29, v8
	v_fma_f32 v7, -v7, v28, v9
	v_div_fmas_f32 v7, v7, v8, v28
	v_div_fixup_f32 v6, v7, v6, 1.0
	v_mul_f32_e32 v6, v166, v6
	v_pk_mul_f32 v[8:9], v[90:91], v[6:7] op_sel_hi:[1,0]
	v_pk_mul_f32 v[4:5], v[4:5], v[6:7] op_sel_hi:[1,0]
	s_waitcnt vmcnt(0)
; DI unsigned pk2(float lo, float hi) { f32x2 v = {lo, hi}; bf16x2_t b = __builtin_convertvector(v, bf16x2_t); return __builtin_bit_cast(unsigned, b); }
; DI void attn_unit(LAS unsigned char* lds, int tid, const bf16* __restrict__ P, const bf16* __restrict__ Vt, bf16* MG, int b, int h, int qrow0, int jt0, int jt1,
;                   float lam, float oscale, const float* subg) {
;     ...
; #pragma unroll
;         for (int es = 0; es < 4; ++es)
; #pragma unroll
;             for (int g4 = 0; g4 < 4; ++g4) {
;                 const int e = es * 32 + 8 * g4 + 4 * hi;
;                 const f32x4 gv = *(const f32x4*)(subg + e);
;                 u32x2 w; w.x = pk2(O[es][4 * g4 + 0] * rn * gv.x, O[es][4 * g4 + 1] * rn * gv.y); w.y = pk2(O[es][4 * g4 + 2] * rn * gv.z, O[es][4 * g4 + 3] * rn * gv.w);
;                 *(u32x2*)(MG + (size_t)qrow * DM + h * 128 + e) = w;
;             }
	v_pk_mul_f32 v[8:9], v[10:11], v[8:9]
	v_pk_mul_f32 v[10:11], v[82:83], v[6:7] op_sel_hi:[1,0]
	v_cvt_pk_bf16_f32 v8, v8, v9
	v_pk_mul_f32 v[10:11], v[12:13], v[10:11]
	v_pk_mul_f32 v[12:13], v[104:105], v[6:7] op_sel_hi:[1,0]
	v_cvt_pk_bf16_f32 v9, v10, v11
	global_store_dwordx2 v[48:49], v[8:9], off
	v_pk_mul_f32 v[2:3], v[2:3], v[6:7] op_sel_hi:[1,0]
	v_pk_mul_f32 v[0:1], v[0:1], v[6:7] op_sel_hi:[1,0]
	v_pk_mul_f32 v[168:169], v[168:169], v[12:13]
	v_pk_mul_f32 v[12:13], v[96:97], v[6:7] op_sel_hi:[1,0]
	v_cvt_pk_bf16_f32 v168, v168, v169
	v_pk_mul_f32 v[170:171], v[170:171], v[12:13]
	v_pk_mul_f32 v[12:13], v[106:107], v[6:7] op_sel_hi:[1,0]
	v_cvt_pk_bf16_f32 v169, v170, v171
	global_store_dwordx2 v[48:49], v[168:169], off offset:16
	v_pk_mul_f32 v[172:173], v[172:173], v[12:13]
	v_pk_mul_f32 v[12:13], v[88:89], v[6:7] op_sel_hi:[1,0]
	v_cvt_pk_bf16_f32 v172, v172, v173
	v_pk_mul_f32 v[174:175], v[174:175], v[12:13]
	v_pk_mul_f32 v[12:13], v[60:61], v[6:7] op_sel_hi:[1,0]
	v_cvt_pk_bf16_f32 v173, v174, v175
	global_store_dwordx2 v[48:49], v[172:173], off offset:32
	v_pk_mul_f32 v[176:177], v[176:177], v[12:13]
	v_pk_mul_f32 v[12:13], v[62:63], v[6:7] op_sel_hi:[1,0]
	v_cvt_pk_bf16_f32 v176, v176, v177
	v_pk_mul_f32 v[178:179], v[178:179], v[12:13]
	v_pk_mul_f32 v[12:13], v[58:59], v[6:7] op_sel_hi:[1,0]
	v_cvt_pk_bf16_f32 v177, v178, v179
	global_store_dwordx2 v[48:49], v[176:177], off offset:48
	v_pk_mul_f32 v[180:181], v[180:181], v[12:13]
	v_pk_mul_f32 v[12:13], v[56:57], v[6:7] op_sel_hi:[1,0]
	v_cvt_pk_bf16_f32 v180, v180, v181
	v_pk_mul_f32 v[182:183], v[182:183], v[12:13]
	v_pk_mul_f32 v[12:13], v[54:55], v[6:7] op_sel_hi:[1,0]
	v_cvt_pk_bf16_f32 v181, v182, v183
	global_store_dwordx2 v[48:49], v[180:181], off offset:64
	v_pk_mul_f32 v[184:185], v[12:13], v[184:185]
	v_pk_mul_f32 v[12:13], v[50:51], v[6:7] op_sel_hi:[1,0]
	v_cvt_pk_bf16_f32 v184, v184, v185
	v_pk_mul_f32 v[186:187], v[12:13], v[186:187]
	v_pk_mul_f32 v[12:13], v[52:53], v[6:7] op_sel_hi:[1,0]
	v_cvt_pk_bf16_f32 v185, v186, v187
	global_store_dwordx2 v[48:49], v[184:185], off offset:80
	v_pk_mul_f32 v[188:189], v[12:13], v[188:189]
	v_pk_mul_f32 v[12:13], v[42:43], v[6:7] op_sel_hi:[1,0]
	v_cvt_pk_bf16_f32 v188, v188, v189
	v_pk_mul_f32 v[190:191], v[12:13], v[190:191]
	v_pk_mul_f32 v[12:13], v[44:45], v[6:7] op_sel_hi:[1,0]
	v_cvt_pk_bf16_f32 v189, v190, v191
	global_store_dwordx2 v[48:49], v[188:189], off offset:96
	v_pk_mul_f32 v[192:193], v[12:13], v[192:193]
	v_pk_mul_f32 v[12:13], v[40:41], v[6:7] op_sel_hi:[1,0]
	v_cvt_pk_bf16_f32 v192, v192, v193
	v_pk_mul_f32 v[194:195], v[12:13], v[194:195]
	v_pk_mul_f32 v[12:13], v[38:39], v[6:7] op_sel_hi:[1,0]
	v_cvt_pk_bf16_f32 v193, v194, v195
	global_store_dwordx2 v[48:49], v[192:193], off offset:112
	v_pk_mul_f32 v[196:197], v[12:13], v[196:197]
	v_pk_mul_f32 v[12:13], v[36:37], v[6:7] op_sel_hi:[1,0]
	v_cvt_pk_bf16_f32 v196, v196, v197
	v_pk_mul_f32 v[198:199], v[12:13], v[198:199]
	v_pk_mul_f32 v[12:13], v[34:35], v[6:7] op_sel_hi:[1,0]
	v_cvt_pk_bf16_f32 v197, v198, v199
	global_store_dwordx2 v[48:49], v[196:197], off offset:128
	v_pk_mul_f32 v[200:201], v[12:13], v[200:201]
	v_pk_mul_f32 v[12:13], v[32:33], v[6:7] op_sel_hi:[1,0]
	v_cvt_pk_bf16_f32 v200, v200, v201
	v_pk_mul_f32 v[202:203], v[12:13], v[202:203]
	v_pk_mul_f32 v[12:13], v[26:27], v[6:7] op_sel_hi:[1,0]
	v_cvt_pk_bf16_f32 v201, v202, v203
	global_store_dwordx2 v[48:49], v[200:201], off offset:144
	v_pk_mul_f32 v[204:205], v[12:13], v[204:205]
	v_pk_mul_f32 v[12:13], v[22:23], v[6:7] op_sel_hi:[1,0]
	v_cvt_pk_bf16_f32 v204, v204, v205
	v_pk_mul_f32 v[206:207], v[12:13], v[206:207]
	v_pk_mul_f32 v[12:13], v[24:25], v[6:7] op_sel_hi:[1,0]
	v_cvt_pk_bf16_f32 v205, v206, v207
	global_store_dwordx2 v[48:49], v[204:205], off offset:160
	v_pk_mul_f32 v[218:219], v[12:13], v[218:219]
	v_pk_mul_f32 v[12:13], v[20:21], v[6:7] op_sel_hi:[1,0]
	v_cvt_pk_bf16_f32 v218, v218, v219
	v_pk_mul_f32 v[220:221], v[12:13], v[220:221]
	v_pk_mul_f32 v[12:13], v[18:19], v[6:7] op_sel_hi:[1,0]
	v_cvt_pk_bf16_f32 v219, v220, v221
	global_store_dwordx2 v[48:49], v[218:219], off offset:176
	v_pk_mul_f32 v[222:223], v[12:13], v[222:223]
	v_pk_mul_f32 v[12:13], v[16:17], v[6:7] op_sel_hi:[1,0]
	v_cvt_pk_bf16_f32 v222, v222, v223
	v_pk_mul_f32 v[224:225], v[12:13], v[224:225]
	s_nop 0
	v_cvt_pk_bf16_f32 v223, v224, v225
	global_store_dwordx2 v[48:49], v[222:223], off offset:192
	v_pk_mul_f32 v[4:5], v[4:5], v[226:227]
	v_pk_mul_f32 v[2:3], v[2:3], v[228:229]
	v_cvt_pk_bf16_f32 v4, v4, v5
	v_cvt_pk_bf16_f32 v5, v2, v3
	global_store_dwordx2 v[48:49], v[4:5], off offset:208
	v_pk_mul_f32 v[0:1], v[0:1], v[230:231]
	v_pk_mul_f32 v[230:231], v[64:65], v[6:7] op_sel_hi:[1,0]
	v_cvt_pk_bf16_f32 v0, v0, v1
	v_pk_mul_f32 v[230:231], v[230:231], v[232:233]
	v_pk_mul_f32 v[232:233], v[66:67], v[6:7] op_sel_hi:[1,0]
	v_cvt_pk_bf16_f32 v1, v230, v231
	global_store_dwordx2 v[48:49], v[0:1], off offset:224
	v_pk_mul_f32 v[234:235], v[232:233], v[234:235]
	v_pk_mul_f32 v[232:233], v[14:15], v[6:7] op_sel_hi:[1,0]
	v_cvt_pk_bf16_f32 v234, v234, v235
	v_pk_mul_f32 v[236:237], v[232:233], v[236:237]
	s_nop 0
	v_cvt_pk_bf16_f32 v235, v236, v237
	global_store_dwordx2 v[48:49], v[234:235], off offset:240
	v_mov_b32_e32 v0, v234
	v_mov_b32_e32 v1, v235
	v_mov_b32_e32 v2, v236
	v_mov_b32_e32 v3, v237
	v_mov_b32_e32 v4, v232
	v_mov_b32_e32 v5, v233
	v_mov_b32_e32 v8, v226
	v_mov_b32_e32 v9, v227
	v_mov_b32_e32 v10, v228
	v_mov_b32_e32 v11, v229
	s_branch .LBB0_294
